# barrier spin without s_sleep between polls
# baseline (speedup 1.0000x reference)
.Lb_spin:
	global_load_dword v4, v1, s[36:37] sc1
	s_waitcnt vmcnt(0)
	v_readfirstlane_b32 s13, v4
	s_cmp_lg_u32 s13, s16
	s_cbranch_scc1 .Lb_done
	s_add_i32 s12, s12, 1
	s_cmp_lt_u32 s12, 0x800
	s_cbranch_scc1 .Lb_spin
